# retention prompt loop: scores+cross MFMA stage hand-scheduled straight-line, 8-deep LDS fragment ring with counted lgkmcnt (same k order, same math)
# speedup vs baseline: 1.0092x; 1.0092x over previous
; template <int DK, int MODE>
; __device__ void rec_prompt_item(const Params& p, const int item, unsigned char* smem) {
;     ...
; #pragma unroll
;     for (int mf = 0; mf < MF; ++mf)
; #pragma unroll
;       for (int nf = 0; nf < 4; ++nf) {
;         u32x2 o;
;         o.x = pack2(S[mf][nf][0], S[mf][nf][1]);
;         o.y = pack2(S[mf][nf][2], S[mf][nf][3]);
;         *(u32x2*)(STs + (16 * nf + l15) * QS + (dw + 16 * mf + 4 * g) * 2) = o;
;       }
;     u16 gzc[2][4];
; #pragma unroll
;     for (int x = 0; x < 2; ++x)
; #pragma unroll
;       for (int r = 0; r < 4; ++r) gzc[x][r] = gz[par][x][r];
;     __syncthreads();
;     if (c + NSET < 32) PF_ISSUE(par, r0 + 64 * NSET)
;     f32x4 sc[2], cr[2];
; #pragma unroll
;     for (int x = 0; x < 2; ++x) { sc[x] = (f32x4){0.f, 0.f, 0.f, 0.f}; cr[x] = (f32x4){0.f, 0.f, 0.f, 0.f}; }
; #pragma unroll KUNR
;     for (int ks = 0; ks < KS; ++ks) {
;       const bf16x8 a = *(const bf16x8*)(Qs + (16 * fi + l15) * QS + ks * 64 + g * 16);
;       bf16x8 bk[2], bs[2];
; #pragma unroll
;       for (int x = 0; x < 2; ++x) {
;         bk[x] = *(const bf16x8*)(Ks + (16 * (fe0 + x) + l15) * QS + ks * 64 + g * 16);
;         bs[x] = *(const bf16x8*)(STs + (16 * (fe0 + x) + l15) * QS + ks * 64 + g * 16);
;       }
; #pragma unroll
;       for (int x = 0; x < 2; ++x) {
;         sc[x] = __builtin_amdgcn_mfma_f32_16x16x32_bf16(a, bk[x], sc[x], 0, 0, 0);
;         cr[x] = __builtin_amdgcn_mfma_f32_16x16x32_bf16(a, bs[x], cr[x], 0, 0, 0);
;       }
;     }
.LBB0_422:
	s_or_b64 exec, exec, s[20:21]
	s_lshl_b32 s20, s43, 6
	s_add_i32 s20, s20, s42
	s_mul_i32 s21, s20, 0x3080
	s_add_u32 s21, s30, s21
	s_addc_u32 s48, s31, 0
	v_cvt_pk_bf16_f32 v0, v64, v65
	v_cvt_pk_bf16_f32 v1, v66, v67
	v_cvt_pk_bf16_f32 v2, v60, v61
	v_cvt_pk_bf16_f32 v3, v62, v63
	s_add_u32 s44, s21, 0xc2000
	ds_write2st64_b64 v189, v[0:1], v[2:3] offset1:17
	v_cvt_pk_bf16_f32 v0, v56, v57
	v_cvt_pk_bf16_f32 v1, v58, v59
	v_cvt_pk_bf16_f32 v2, v52, v53
	v_cvt_pk_bf16_f32 v3, v54, v55
	s_addc_u32 s45, s48, 0
	ds_write2st64_b64 v189, v[0:1], v[2:3] offset0:34 offset1:51
	v_cvt_pk_bf16_f32 v0, v48, v49
	v_cvt_pk_bf16_f32 v1, v50, v51
	v_cvt_pk_bf16_f32 v2, v44, v45
	v_cvt_pk_bf16_f32 v3, v46, v47
	s_add_u32 s46, s21, 0xc2800
	ds_write2st64_b64 v190, v[0:1], v[2:3] offset1:17
	v_cvt_pk_bf16_f32 v0, v40, v41
	v_cvt_pk_bf16_f32 v1, v42, v43
	v_cvt_pk_bf16_f32 v2, v36, v37
	v_cvt_pk_bf16_f32 v3, v38, v39
	s_addc_u32 s47, s48, 0
	ds_write2st64_b64 v190, v[0:1], v[2:3] offset0:34 offset1:51
	v_lshl_add_u64 v[0:1], s[44:45], 0, v[98:99]
	v_lshl_add_u64 v[2:3], s[46:47], 0, v[98:99]
	v_lshl_add_u64 v[8:9], s[44:45], 0, v[118:119]
	v_lshl_add_u64 v[10:11], s[46:47], 0, v[118:119]
	v_lshl_add_u64 v[16:17], s[44:45], 0, v[120:121]
	v_lshl_add_u64 v[18:19], s[46:47], 0, v[120:121]
	v_lshl_add_u64 v[24:25], s[44:45], 0, v[122:123]
	v_lshl_add_u64 v[26:27], s[46:47], 0, v[122:123]
	v_lshl_add_u64 v[28:29], s[44:45], 0, v[132:133]
	v_lshl_add_u64 v[68:69], s[44:45], 0, v[124:125]
	s_waitcnt lgkmcnt(0)
	s_barrier
	global_load_dwordx4 v[4:7], v[0:1], off
	s_nop 0
	global_load_dwordx4 v[0:3], v[2:3], off
	s_nop 0
	global_load_dwordx4 v[12:15], v[8:9], off
	s_nop 0
	global_load_dwordx4 v[8:11], v[10:11], off
	s_nop 0
	global_load_dwordx4 v[20:23], v[16:17], off
	s_nop 0
	global_load_dwordx4 v[16:19], v[18:19], off
	s_nop 0
	global_load_dwordx4 v[32:35], v[24:25], off
	s_nop 0
	global_load_dwordx4 v[24:27], v[26:27], off
	v_lshl_add_u64 v[70:71], s[44:45], 0, v[126:127]
	v_lshl_add_u64 v[72:73], s[44:45], 0, v[128:129]
	global_load_dwordx4 v[28:31], v[28:29], off
	s_nop 0
	global_load_ushort v216, v[68:69], off
	global_load_ushort v215, v[70:71], off
	global_load_ushort v214, v[72:73], off
	v_lshl_add_u64 v[68:69], s[44:45], 0, v[130:131]
	s_add_u32 s44, s21, 0xc2020
	s_addc_u32 s45, s48, 0
	v_lshl_add_u64 v[70:71], s[44:45], 0, v[124:125]
	v_lshl_add_u64 v[72:73], s[44:45], 0, v[126:127]
	v_lshl_add_u64 v[74:75], s[44:45], 0, v[128:129]
	v_lshl_add_u64 v[76:77], s[44:45], 0, v[130:131]
	global_load_ushort v213, v[68:69], off
	global_load_ushort v212, v[70:71], off
	global_load_ushort v211, v[72:73], off
	global_load_ushort v210, v[74:75], off
	global_load_ushort v209, v[76:77], off
	v_add_u32_e32 v217, 0x11000, v177
	v_add_u32_e32 v242, 0x11000, v176
	ds_read_b128 v[218:221], v178
	ds_read_b128 v[222:225], v177 offset:34816
	ds_read_b128 v[226:229], v217
	ds_read_b128 v[230:233], v176 offset:34816
	ds_read_b128 v[234:237], v242
	ds_read_b128 v[238:241], v178 offset:64
	ds_read_b128 v[76:79], v177 offset:34880
	ds_read_b128 v[248:251], v217 offset:64
	s_waitcnt lgkmcnt(6)
	v_mfma_f32_16x16x32_bf16 v[84:87], v[218:221], v[222:225], 0
	ds_read_b128 v[222:225], v176 offset:34880
	s_waitcnt lgkmcnt(6)
	v_mfma_f32_16x16x32_bf16 v[72:75], v[218:221], v[226:229], 0
	ds_read_b128 v[226:229], v242 offset:64
	s_waitcnt lgkmcnt(6)
	v_mfma_f32_16x16x32_bf16 v[80:83], v[218:221], v[230:233], 0
	ds_read_b128 v[230:233], v178 offset:128
	s_waitcnt lgkmcnt(6)
	v_mfma_f32_16x16x32_bf16 v[68:71], v[218:221], v[234:237], 0
	ds_read_b128 v[234:237], v177 offset:34944
	ds_read_b128 v[218:221], v217 offset:128
	s_waitcnt lgkmcnt(6)
	v_mfma_f32_16x16x32_bf16 v[84:87], v[238:241], v[76:79], v[84:87]
	ds_read_b128 v[76:79], v176 offset:34944
	s_waitcnt lgkmcnt(6)
	v_mfma_f32_16x16x32_bf16 v[72:75], v[238:241], v[248:251], v[72:75]
	ds_read_b128 v[248:251], v242 offset:128
	s_waitcnt lgkmcnt(6)
	v_mfma_f32_16x16x32_bf16 v[80:83], v[238:241], v[222:225], v[80:83]
	ds_read_b128 v[222:225], v178 offset:192
	s_waitcnt lgkmcnt(6)
	v_mfma_f32_16x16x32_bf16 v[68:71], v[238:241], v[226:229], v[68:71]
	ds_read_b128 v[226:229], v177 offset:35008
	ds_read_b128 v[238:241], v217 offset:192
	s_waitcnt lgkmcnt(6)
	v_mfma_f32_16x16x32_bf16 v[84:87], v[230:233], v[234:237], v[84:87]
	ds_read_b128 v[234:237], v176 offset:35008
	s_waitcnt lgkmcnt(6)
	v_mfma_f32_16x16x32_bf16 v[72:75], v[230:233], v[218:221], v[72:75]
	ds_read_b128 v[218:221], v242 offset:192
	s_waitcnt lgkmcnt(6)
	v_mfma_f32_16x16x32_bf16 v[80:83], v[230:233], v[76:79], v[80:83]
	ds_read_b128 v[76:79], v178 offset:256
	s_waitcnt lgkmcnt(6)
	v_mfma_f32_16x16x32_bf16 v[68:71], v[230:233], v[248:251], v[68:71]
	ds_read_b128 v[248:251], v177 offset:35072
	ds_read_b128 v[230:233], v217 offset:256
	s_waitcnt lgkmcnt(6)
	v_mfma_f32_16x16x32_bf16 v[84:87], v[222:225], v[226:229], v[84:87]
	ds_read_b128 v[226:229], v176 offset:35072
	s_waitcnt lgkmcnt(6)
	v_mfma_f32_16x16x32_bf16 v[72:75], v[222:225], v[238:241], v[72:75]
	ds_read_b128 v[238:241], v242 offset:256
	s_waitcnt lgkmcnt(6)
	v_mfma_f32_16x16x32_bf16 v[80:83], v[222:225], v[234:237], v[80:83]
	ds_read_b128 v[234:237], v178 offset:320
	s_waitcnt lgkmcnt(6)
	v_mfma_f32_16x16x32_bf16 v[68:71], v[222:225], v[218:221], v[68:71]
	ds_read_b128 v[218:221], v177 offset:35136
	ds_read_b128 v[222:225], v217 offset:320
	s_waitcnt lgkmcnt(6)
	v_mfma_f32_16x16x32_bf16 v[84:87], v[76:79], v[248:251], v[84:87]
	ds_read_b128 v[248:251], v176 offset:35136
	s_waitcnt lgkmcnt(6)
	v_mfma_f32_16x16x32_bf16 v[72:75], v[76:79], v[230:233], v[72:75]
	ds_read_b128 v[230:233], v242 offset:320
	s_waitcnt lgkmcnt(6)
; __device__ __forceinline__ float ex2(float x) { return __builtin_amdgcn_exp2f(x); }
; template <int DK, int MODE>
; __device__ void rec_prompt_item(const Params& p, const int item, unsigned char* smem) {
;     ...
;     for (int ks = 0; ks < KS; ++ks) {
;       const bf16x8 a = *(const bf16x8*)(Qs + (16 * fi + l15) * QS + ks * 64 + g * 16);
;       bf16x8 bk[2], bs[2];
; #pragma unroll
;       for (int x = 0; x < 2; ++x) {
;         bk[x] = *(const bf16x8*)(Ks + (16 * (fe0 + x) + l15) * QS + ks * 64 + g * 16);
;         bs[x] = *(const bf16x8*)(STs + (16 * (fe0 + x) + l15) * QS + ks * 64 + g * 16);
;       }
; #pragma unroll
;       for (int x = 0; x < 2; ++x) {
;         sc[x] = __builtin_amdgcn_mfma_f32_16x16x32_bf16(a, bk[x], sc[x], 0, 0, 0);
;         cr[x] = __builtin_amdgcn_mfma_f32_16x16x32_bf16(a, bs[x], cr[x], 0, 0, 0);
;       }
;     }
;     float ci[4];
; #pragma unroll
;     for (int r = 0; r < 4; ++r) ci[r] = cumS[16 * fi + 4 * g + r];
; #pragma unroll
;     for (int x = 0; x < 2; ++x) {
;       const int fj = fe0 + x;
;       const int j = 16 * fj + l15;
;       const float cj = cumS[j], uj = uS[j];
; #pragma unroll
;       for (int r = 0; r < 4; ++r) {
;         const int i = 16 * fi + 4 * g + r;
;         float v = 0.f;
;         if (j <= i) v = sc[x][r] * ex2(ci[r] - cj) * uj;
;         *(u16*)(Ps + i * PS + j * 2) = f2bf(v);
;       }
;     }
;     {
;       const float atot = ex2(cumS[63]);
; #pragma unroll
;       for (int mf = 0; mf < MF; ++mf)
; #pragma unroll
;         for (int nf = 0; nf < 4; ++nf)
; #pragma unroll
;           for (int r = 0; r < 4; ++r) S[mf][nf][r] *= atot;
; #pragma unroll
;       for (int ks = 0; ks < 2; ++ks) {
;         bf16x8 af[MF], bfv[4];
; #pragma unroll
;         for (int mf = 0; mf < MF; ++mf) af[mf] = trfrag(Ks, QS, 32 * ks, dw + 16 * mf, lane);
; #pragma unroll
;         for (int nf = 0; nf < 4; ++nf) bfv[nf] = trfrag(Vts, VS, 32 * ks, 16 * nf, lane);
; #pragma unroll
;         for (int mf = 0; mf < MF; ++mf)
; #pragma unroll
;           for (int nf = 0; nf < 4; ++nf)
;             S[mf][nf] = __builtin_amdgcn_mfma_f32_16x16x32_bf16(af[mf], bfv[nf], S[mf][nf], 0, 0, 0);
;       }
	v_mfma_f32_16x16x32_bf16 v[80:83], v[76:79], v[226:229], v[80:83]
	ds_read_b128 v[226:229], v178 offset:384
	s_waitcnt lgkmcnt(6)
	v_mfma_f32_16x16x32_bf16 v[68:71], v[76:79], v[238:241], v[68:71]
	ds_read_b128 v[238:241], v177 offset:35200
	ds_read_b128 v[76:79], v217 offset:384
	s_waitcnt lgkmcnt(6)
	v_mfma_f32_16x16x32_bf16 v[84:87], v[234:237], v[218:221], v[84:87]
	ds_read_b128 v[218:221], v176 offset:35200
	s_waitcnt lgkmcnt(6)
	v_mfma_f32_16x16x32_bf16 v[72:75], v[234:237], v[222:225], v[72:75]
	ds_read_b128 v[222:225], v242 offset:384
	s_waitcnt lgkmcnt(6)
	v_mfma_f32_16x16x32_bf16 v[80:83], v[234:237], v[248:251], v[80:83]
	ds_read_b128 v[248:251], v178 offset:448
	s_waitcnt lgkmcnt(6)
	v_mfma_f32_16x16x32_bf16 v[68:71], v[234:237], v[230:233], v[68:71]
	ds_read_b128 v[230:233], v177 offset:35264
	ds_read_b128 v[234:237], v217 offset:448
	s_waitcnt lgkmcnt(6)
	v_mfma_f32_16x16x32_bf16 v[84:87], v[226:229], v[238:241], v[84:87]
	ds_read_b128 v[238:241], v176 offset:35264
	s_waitcnt lgkmcnt(6)
	v_mfma_f32_16x16x32_bf16 v[72:75], v[226:229], v[76:79], v[72:75]
	ds_read_b128 v[76:79], v242 offset:448
	s_waitcnt lgkmcnt(6)
	v_mfma_f32_16x16x32_bf16 v[80:83], v[226:229], v[218:221], v[80:83]
	s_waitcnt lgkmcnt(5)
	v_mfma_f32_16x16x32_bf16 v[68:71], v[226:229], v[222:225], v[68:71]
	s_waitcnt lgkmcnt(3)
	v_mfma_f32_16x16x32_bf16 v[84:87], v[248:251], v[230:233], v[84:87]
	s_waitcnt lgkmcnt(2)
	v_mfma_f32_16x16x32_bf16 v[72:75], v[248:251], v[234:237], v[72:75]
	s_waitcnt lgkmcnt(1)
	v_mfma_f32_16x16x32_bf16 v[80:83], v[248:251], v[238:241], v[80:83]
	s_waitcnt lgkmcnt(0)
	v_mfma_f32_16x16x32_bf16 v[68:71], v[248:251], v[76:79], v[68:71]
	s_movk_i32 s21, 0x200
	s_cmpk_eq_i32 s21, 0x200
	ds_read_b128 v[76:79], v191
	ds_read_b32 v194, v167
	ds_read_b32 v217, v168
	ds_read_b32 v218, v169
	ds_read_b32 v219, v170
	ds_read_b32 v220, v188
	s_waitcnt lgkmcnt(4)
	v_sub_f32_e32 v221, v76, v194
	v_exp_f32_e32 v221, v221
	v_sub_f32_e32 v222, v77, v194
	v_exp_f32_e32 v222, v222
	s_lshl_b32 s21, s20, 12
	v_mul_f32_e32 v84, v84, v221
	s_waitcnt lgkmcnt(3)
	v_mul_f32_e32 v84, v217, v84
	v_cvt_pk_bf16_f32 v84, v84, s0
	v_cndmask_b32_e64 v84, v84, 0, s[4:5]
	ds_write_b16 v192, v84
	v_mul_f32_e32 v84, v85, v222
	v_sub_f32_e32 v85, v78, v194
	v_exp_f32_e32 v85, v85
	v_mul_f32_e32 v84, v217, v84
	v_cvt_pk_bf16_f32 v84, v84, s0
	v_cndmask_b32_e64 v84, v84, 0, s[6:7]
	ds_write_b16 v192, v84 offset:144
	v_mul_f32_e32 v84, v86, v85
	v_sub_f32_e32 v85, v79, v194
	v_exp_f32_e32 v85, v85
	v_mul_f32_e32 v84, v217, v84
	v_cvt_pk_bf16_f32 v84, v84, s0
	v_cndmask_b32_e64 v84, v84, 0, s[8:9]
	ds_write_b16 v192, v84 offset:288
	v_mul_f32_e32 v84, v87, v85
	s_waitcnt lgkmcnt(5)
	v_sub_f32_e32 v85, v76, v218
	v_mul_f32_e32 v84, v217, v84
	v_exp_f32_e32 v85, v85
	v_cvt_pk_bf16_f32 v84, v84, s0
	v_cndmask_b32_e64 v84, v84, 0, s[10:11]
	ds_write_b16 v192, v84 offset:432
	v_sub_f32_e32 v84, v77, v218
	v_mul_f32_e32 v80, v80, v85
	v_exp_f32_e32 v84, v84
	s_waitcnt lgkmcnt(5)
	v_mul_f32_e32 v80, v219, v80
	v_cvt_pk_bf16_f32 v80, v80, s0
	v_cndmask_b32_e64 v80, v80, 0, s[12:13]
	ds_write_b16 v193, v80
	v_mul_f32_e32 v80, v81, v84
	v_sub_f32_e32 v81, v78, v218
	v_exp_f32_e32 v81, v81
	v_mul_f32_e32 v80, v219, v80
	v_cvt_pk_bf16_f32 v80, v80, s0
	v_cndmask_b32_e64 v80, v80, 0, s[14:15]
	ds_write_b16 v193, v80 offset:144
	v_mul_f32_e32 v80, v82, v81
	v_sub_f32_e32 v81, v79, v218
	v_exp_f32_e32 v81, v81
	v_mul_f32_e32 v80, v219, v80
	v_cvt_pk_bf16_f32 v80, v80, s0
	v_cndmask_b32_e64 v80, v80, 0, s[16:17]
	ds_write_b16 v193, v80 offset:288
	v_mul_f32_e32 v80, v83, v81
	v_mul_f32_e32 v80, v219, v80
	v_cvt_pk_bf16_f32 v80, v80, s0
	v_cndmask_b32_e64 v80, v80, 0, s[18:19]
	ds_write_b16 v193, v80 offset:432
	s_waitcnt lgkmcnt(8)
	v_exp_f32_e32 v194, v220
	ds_read_b64_tr_b16 v[82:83], v195 offset:36992
	ds_read_b64_tr_b16 v[80:81], v195 offset:34816
	ds_read_b64_tr_b16 v[86:87], v195 offset:37024
	ds_read_b64_tr_b16 v[84:85], v195 offset:34848
	ds_read_b64_tr_b16 v[220:221], v196 offset:640
	ds_read_b64_tr_b16 v[218:219], v196
	ds_read_b64_tr_b16 v[222:223], v196 offset:32
	ds_read_b64_tr_b16 v[226:227], v196 offset:64
	ds_read_b64_tr_b16 v[230:231], v196 offset:96
	ds_read_b64_tr_b16 v[224:225], v196 offset:672
	ds_read_b64_tr_b16 v[228:229], v196 offset:704
	ds_read_b64_tr_b16 v[232:233], v196 offset:736
	v_add_u32_e32 v217, v163, v164
	s_add_u32 s44, s33, s21
	v_pk_mul_f32 v[66:67], v[66:67], v[194:195] op_sel_hi:[1,0]
	v_pk_mul_f32 v[64:65], v[64:65], v[194:195] op_sel_hi:[1,0]
	v_pk_mul_f32 v[62:63], v[62:63], v[194:195] op_sel_hi:[1,0]
	v_pk_mul_f32 v[60:61], v[60:61], v[194:195] op_sel_hi:[1,0]
	v_pk_mul_f32 v[58:59], v[58:59], v[194:195] op_sel_hi:[1,0]
	v_pk_mul_f32 v[56:57], v[56:57], v[194:195] op_sel_hi:[1,0]
	v_pk_mul_f32 v[54:55], v[54:55], v[194:195] op_sel_hi:[1,0]
	v_pk_mul_f32 v[52:53], v[52:53], v[194:195] op_sel_hi:[1,0]
	v_pk_mul_f32 v[50:51], v[50:51], v[194:195] op_sel_hi:[1,0]
	v_pk_mul_f32 v[48:49], v[48:49], v[194:195] op_sel_hi:[1,0]
	v_pk_mul_f32 v[46:47], v[46:47], v[194:195] op_sel_hi:[1,0]
	v_pk_mul_f32 v[44:45], v[44:45], v[194:195] op_sel_hi:[1,0]
	v_pk_mul_f32 v[42:43], v[42:43], v[194:195] op_sel_hi:[1,0]
	v_pk_mul_f32 v[40:41], v[40:41], v[194:195] op_sel_hi:[1,0]
	v_pk_mul_f32 v[38:39], v[38:39], v[194:195] op_sel_hi:[1,0]
	v_pk_mul_f32 v[36:37], v[36:37], v[194:195] op_sel_hi:[1,0]
	s_waitcnt lgkmcnt(6)
	v_mfma_f32_16x16x32_bf16 v[64:67], v[80:83], v[218:221], v[64:67]
	s_waitcnt vmcnt(24)
	v_lshlrev_b32_e32 v194, 16, v208
	v_mul_f32_e32 v208, 0xbfb8aa3b, v194
	v_exp_f32_e32 v208, v208
	s_waitcnt lgkmcnt(2)
	v_mfma_f32_16x16x32_bf16 v[60:63], v[80:83], v[222:225], v[60:63]
	s_addc_u32 s45, s34, 0
	s_waitcnt lgkmcnt(1)
	v_mfma_f32_16x16x32_bf16 v[56:59], v[80:83], v[226:229], v[56:59]
	s_waitcnt lgkmcnt(0)
	v_mfma_f32_16x16x32_bf16 v[52:55], v[80:83], v[230:233], v[52:55]
	v_mfma_f32_16x16x32_bf16 v[48:51], v[84:87], v[218:221], v[48:51]
	v_mfma_f32_16x16x32_bf16 v[44:47], v[84:87], v[222:225], v[44:47]
	v_mfma_f32_16x16x32_bf16 v[80:83], v[84:87], v[226:229], v[40:43]
	v_mfma_f32_16x16x32_bf16 v[84:87], v[84:87], v[230:233], v[36:39]
	s_nop 2
	ds_read_b64_tr_b16 v[38:39], v197 offset:36992
	ds_read_b64_tr_b16 v[36:37], v197 offset:34816
	ds_read_b64_tr_b16 v[220:221], v197 offset:37024
	ds_read_b64_tr_b16 v[218:219], v197 offset:34848
	ds_read_b64_tr_b16 v[42:43], v196 offset:5760
	ds_read_b64_tr_b16 v[40:41], v196 offset:5120
	ds_read_b64_tr_b16 v[222:223], v196 offset:5152
	ds_read_b64_tr_b16 v[226:227], v196 offset:5184
	ds_read_b64_tr_b16 v[230:231], v196 offset:5216
	ds_read_b64_tr_b16 v[224:225], v196 offset:5792
	ds_read_b64_tr_b16 v[228:229], v196 offset:5824
	ds_read_b64_tr_b16 v[232:233], v196 offset:5856
	s_waitcnt lgkmcnt(0)
	s_barrier
; template <int DK, int MODE>
; __device__ void rec_prompt_item(const Params& p, const int item, unsigned char* smem) {
;     ...
;         for (int mf = 0; mf < MF; ++mf) af[mf] = trfrag(Ks, QS, 32 * ks, dw + 16 * mf, lane);
; #pragma unroll
;         for (int nf = 0; nf < 4; ++nf) bfv[nf] = trfrag(Vts, VS, 32 * ks, 16 * nf, lane);
; #pragma unroll
;         for (int mf = 0; mf < MF; ++mf)
; #pragma unroll
;           for (int nf = 0; nf < 4; ++nf)
;             S[mf][nf] = __builtin_amdgcn_mfma_f32_16x16x32_bf16(af[mf], bfv[nf], S[mf][nf], 0, 0, 0);
;       }
;     }
;     __syncthreads();
;     f32x4 in[2];
; #pragma unroll
;     for (int x = 0; x < 2; ++x) in[x] = (f32x4){0.f, 0.f, 0.f, 0.f};
; #pragma unroll
;     for (int ks = 0; ks < 2; ++ks) {
;       const bf16x8 a = *(const bf16x8*)(Ps + (16 * fi + l15) * PS + ks * 64 + g * 16);
;       bf16x8 bv[2];
; #pragma unroll
;       for (int x = 0; x < 2; ++x) bv[x] = trfrag(Vs, VS, 32 * ks, 16 * (fe0 + x), lane);
; #pragma unroll
;       for (int x = 0; x < 2; ++x) in[x] = __builtin_amdgcn_mfma_f32_16x16x32_bf16(a, bv[x], in[x], 0, 0, 0);
;     }
;     {
;       float ss[4] = {0.f, 0.f, 0.f, 0.f};
;       u16* aout = (u16*)(p.ws + OFF_A2);
;       float* parts = (float*)(p.ws + OFF_PARTS);
; #pragma unroll
;       for (int x = 0; x < 2; ++x) {
;         const int e = 16 * (fe0 + x) + l15;
;         const float gn = gnv[x];
;         const int ocol = (MODE == 0) ? (h * 512 + s * 64 + e) : (h * 64 + e);
; #pragma unroll
;         for (int r = 0; r < 4; ++r) {
;           const int i = 16 * fi + 4 * g + r;
;           float o = in[x][r] + cr[x][r] * ex2(ci[r]);
;           const float gv = bf2f(gzc[x][r]);
;           float val;
;           if (MODE == 0) {
;             ss[r] += o * o;
;             val = o * gn * silu(gv);
;           } else {
;             const float xs = bf2f(*(const u16*)(Vs + i * VS + e * 2));
;             const float y = o + xs * dsk;
;             const float gg = y * silu(gv);
;             ss[r] += gg * gg;
;             val = gg * gn;
;           }
;           *(u16*)((char*)aout + (size_t)r0 * 4096 + 32 * x + aoff[r]) = f2bf(val);
;         }
;       }
; #pragma unroll
;       for (int r = 0; r < 4; ++r) {
;         const float v = row16_sum(ss[r]);
;         if (l15 == 0) {
;           const int i = 16 * fi + 4 * g + r;
	v_mfma_f32_16x16x32_bf16 v[64:67], v[36:39], v[40:43], v[64:67]
	v_mfma_f32_16x16x32_bf16 v[60:63], v[36:39], v[222:225], v[60:63]
	v_mfma_f32_16x16x32_bf16 v[56:59], v[36:39], v[226:229], v[56:59]
	v_mfma_f32_16x16x32_bf16 v[52:55], v[36:39], v[230:233], v[52:55]
	v_mfma_f32_16x16x32_bf16 v[36:39], v[218:221], v[226:229], v[80:83]
	s_nop 2
	ds_read_b128 v[80:83], v198
	v_mfma_f32_16x16x32_bf16 v[48:51], v[218:221], v[40:43], v[48:51]
	v_mfma_f32_16x16x32_bf16 v[40:43], v[218:221], v[222:225], v[44:47]
	v_mfma_f32_16x16x32_bf16 v[44:47], v[218:221], v[230:233], v[84:87]
	s_nop 2
	ds_read_b64_tr_b16 v[84:85], v217
	ds_read_b64_tr_b16 v[86:87], v217 offset:640
	v_add_u32_e32 v218, v163, v165
	v_add_u32_e32 v219, v166, v164
	ds_read_b64_tr_b16 v[220:221], v218
	ds_read_b64_tr_b16 v[222:223], v218 offset:640
	ds_read_b128 v[224:227], v198 offset:64
	ds_read_b64_tr_b16 v[228:229], v219
	ds_read_b64_tr_b16 v[230:231], v219 offset:640
	s_waitcnt lgkmcnt(5)
	v_mfma_f32_16x16x32_bf16 v[84:87], v[80:83], v[84:87], 0
	s_waitcnt lgkmcnt(3)
	v_mfma_f32_16x16x32_bf16 v[232:235], v[80:83], v[220:223], 0
	v_exp_f32_e32 v221, v76
	v_add_f32_e32 v76, 1.0, v208
	v_rcp_f32_e32 v76, v76
	s_waitcnt lgkmcnt(0)
	v_mfma_f32_16x16x32_bf16 v[80:83], v[224:227], v[228:231], v[84:87]
	v_add_u32_e32 v220, v166, v165
	v_lshl_add_u64 v[222:223], s[44:45], 0, v[134:135]
	v_mul_f32_e32 v76, v76, v194
	v_exp_f32_e32 v194, v77
	ds_read_b64_tr_b16 v[236:237], v220
	ds_read_b64_tr_b16 v[238:239], v220 offset:640
	s_nop 1
	v_fma_f32 v208, v72, v221, v80
	v_mul_f32_e32 v72, v117, v208
	v_mul_f32_e32 v72, v76, v72
	s_waitcnt vmcnt(23)
	v_lshlrev_b32_e32 v76, 16, v207
	v_mul_f32_e32 v80, 0xbfb8aa3b, v76
	v_exp_f32_e32 v80, v80
	v_cvt_pk_bf16_f32 v72, v72, s0
	v_fma_f32 v73, v73, v194, v81
	global_store_short v[222:223], v72, off
	v_add_f32_e32 v77, 1.0, v80
	v_rcp_f32_e32 v77, v77
	v_mul_f32_e32 v72, v117, v73
	s_waitcnt vmcnt(23)
	v_lshlrev_b32_e32 v80, 16, v206
	v_exp_f32_e32 v206, v78
	v_mul_f32_e32 v76, v77, v76
	v_mul_f32_e32 v72, v76, v72
	v_mul_f32_e32 v76, 0xbfb8aa3b, v80
	v_exp_f32_e32 v81, v76
	v_cvt_pk_bf16_f32 v72, v72, s0
	v_lshl_add_u64 v[76:77], s[44:45], 0, v[136:137]
	global_store_short v[76:77], v72, off
	v_add_f32_e32 v78, 1.0, v81
	v_rcp_f32_e32 v78, v78
	v_fma_f32 v72, v74, v206, v82
	v_mul_f32_e32 v74, v117, v72
	s_waitcnt lgkmcnt(0)
	v_mfma_f32_16x16x32_bf16 v[84:87], v[224:227], v[236:239], v[232:235]
	v_mul_f32_e32 v78, v78, v80
	v_mul_f32_e32 v74, v78, v74
	s_waitcnt vmcnt(23)
	v_lshlrev_b32_e32 v78, 16, v205
	v_mul_f32_e32 v80, 0xbfb8aa3b, v78
	v_exp_f32_e32 v82, v80
	v_exp_f32_e32 v205, v79
	v_cvt_pk_bf16_f32 v74, v74, s0
	v_lshl_add_u64 v[80:81], s[44:45], 0, v[138:139]
	v_add_f32_e32 v79, 1.0, v82
	v_rcp_f32_e32 v79, v79
	v_fmac_f32_e32 v83, v75, v205
	global_store_short v[80:81], v74, off
	v_mul_f32_e32 v74, v117, v83
	v_mul_f32_e32 v75, v79, v78
	v_mul_f32_e32 v74, v75, v74
	v_cvt_pk_bf16_f32 v74, v74, s0
	v_lshl_add_u64 v[78:79], s[44:45], 0, v[140:141]
	global_store_short v[78:79], v74, off
	s_waitcnt vmcnt(24)
	v_lshlrev_b32_e32 v74, 16, v204
	v_mul_f32_e32 v75, 0xbfb8aa3b, v74
	v_exp_f32_e32 v75, v75
	v_fma_f32 v68, v68, v221, v84
	s_waitcnt vmcnt(23)
	v_lshlrev_b32_e32 v84, 16, v203
	v_mul_f32_e32 v203, 0xbfb8aa3b, v84
	v_add_f32_e32 v75, 1.0, v75
	v_rcp_f32_e32 v75, v75
	v_exp_f32_e32 v203, v203
	v_mul_f32_e32 v82, v68, v68
	v_mul_f32_e32 v68, v199, v68
	v_mul_f32_e32 v74, v75, v74
	v_mul_f32_e32 v68, v74, v68
	v_add_f32_e32 v74, 1.0, v203
	v_rcp_f32_e32 v75, v74
	v_cvt_pk_bf16_f32 v68, v68, s0
	v_fma_f32 v74, v69, v194, v85
	global_store_short v[222:223], v68, off offset:32
	v_mul_f32_e32 v68, v199, v74
	v_mul_f32_e32 v69, v75, v84
	v_mul_f32_e32 v68, v69, v68
	s_waitcnt vmcnt(23)
	v_lshlrev_b32_e32 v69, 16, v202
	v_mul_f32_e32 v75, 0xbfb8aa3b, v69
	v_exp_f32_e32 v75, v75
	v_cvt_pk_bf16_f32 v68, v68, s0
	global_store_short v[76:77], v68, off offset:32
	s_waitcnt vmcnt(23)
	v_lshlrev_b32_e32 v76, 16, v201
	v_add_f32_e32 v75, 1.0, v75
	v_rcp_f32_e32 v75, v75
	v_mul_f32_e32 v77, 0xbfb8aa3b, v76
	v_exp_f32_e32 v77, v77
	v_fma_f32 v70, v70, v206, v86
	v_mul_f32_e32 v68, v199, v70
	v_mul_f32_e32 v69, v75, v69
	v_mul_f32_e32 v68, v69, v68
	v_add_f32_e32 v69, 1.0, v77
	v_rcp_f32_e32 v69, v69
	v_cvt_pk_bf16_f32 v68, v68, s0
	v_fmac_f32_e32 v87, v71, v205
	v_fmac_f32_e32 v82, v208, v208
	global_store_short v[80:81], v68, off offset:32
	v_mul_f32_e32 v68, v199, v87
	v_mul_f32_e32 v69, v69, v76
	v_mul_f32_e32 v68, v69, v68
	v_cvt_pk_bf16_f32 v68, v68, s0
	v_add_f32_dpp v69, v82, v82 quad_perm:[1,0,3,2] row_mask:0xf bank_mask:0xf bound_ctrl:1
	global_store_short v[78:79], v68, off offset:32
	v_add_u32_e32 v68, s20, v91
	v_add_f32_dpp v69, v69, v69 quad_perm:[2,3,0,1] row_mask:0xf bank_mask:0xf bound_ctrl:1
	s_nop 1
	v_add_f32_dpp v71, v69, v69 row_ror:4 row_mask:0xf bank_mask:0xf bound_ctrl:1
	s_nop 1
	v_mov_b32_dpp v75, v71 row_ror:8 row_mask:0xf bank_mask:0xf bound_ctrl:1
	s_and_saveexec_b64 s[20:21], s[2:3]
	s_cbranch_execz .LBB0_426
	v_ashrrev_i32_e32 v69, 31, v68
	v_lshlrev_b64 v[76:77], 8, v[68:69]
	v_lshl_add_u64 v[76:77], v[144:145], 0, v[76:77]
	v_add_f32_e32 v69, v71, v75
	global_store_dword v[76:77], v69, off

; __device__ __forceinline__ float ex2(float x) { return __builtin_amdgcn_exp2f(x); }
; template <int DK, int MODE>
; __device__ void rec_prompt_item(const Params& p, const int item, unsigned char* smem) {
;     ...
;     f32x4 sc[2], cr[2];
; #pragma unroll
;     for (int x = 0; x < 2; ++x) { sc[x] = (f32x4){0.f, 0.f, 0.f, 0.f}; cr[x] = (f32x4){0.f, 0.f, 0.f, 0.f}; }
; #pragma unroll KUNR
;     for (int ks = 0; ks < KS; ++ks) {
;       const bf16x8 a = *(const bf16x8*)(Qs + (16 * fi + l15) * QS + ks * 64 + g * 16);
;       bf16x8 bk[2], bs[2];
; #pragma unroll
;       for (int x = 0; x < 2; ++x) {
;         bk[x] = *(const bf16x8*)(Ks + (16 * (fe0 + x) + l15) * QS + ks * 64 + g * 16);
;         bs[x] = *(const bf16x8*)(STs + (16 * (fe0 + x) + l15) * QS + ks * 64 + g * 16);
;       }
; #pragma unroll
;       for (int x = 0; x < 2; ++x) {
;         sc[x] = __builtin_amdgcn_mfma_f32_16x16x32_bf16(a, bk[x], sc[x], 0, 0, 0);
;         cr[x] = __builtin_amdgcn_mfma_f32_16x16x32_bf16(a, bs[x], cr[x], 0, 0, 0);
;       }
;     }
;     float ci[4];
; #pragma unroll
;     for (int r = 0; r < 4; ++r) ci[r] = cumS[16 * fi + 4 * g + r];
; #pragma unroll
;     for (int x = 0; x < 2; ++x) {
;       const int fj = fe0 + x;
;       const int j = 16 * fj + l15;
;       const float cj = cumS[j], uj = uS[j];
; #pragma unroll
;       for (int r = 0; r < 4; ++r) {
;         const int i = 16 * fi + 4 * g + r;
;         float v = 0.f;
;         if (j <= i) v = sc[x][r] * ex2(ci[r] - cj) * uj;
;         *(u16*)(Ps + i * PS + j * 2) = f2bf(v);
;       }
;     }
.LBB0_436:
	v_add_u32_e32 v221, 0x11000, v177
	v_add_u32_e32 v246, 0x11000, v176
	ds_read_b128 v[222:225], v178
	ds_read_b128 v[226:229], v177 offset:34816
	ds_read_b128 v[230:233], v221
	ds_read_b128 v[234:237], v176 offset:34816
	ds_read_b128 v[238:241], v246
	ds_read_b128 v[242:245], v178 offset:64
	ds_read_b128 v[76:79], v177 offset:34880
	ds_read_b128 v[248:251], v221 offset:64
	s_waitcnt lgkmcnt(6)
	v_mfma_f32_16x16x32_bf16 v[84:87], v[222:225], v[226:229], 0
	ds_read_b128 v[226:229], v176 offset:34880
	s_waitcnt lgkmcnt(6)
	v_mfma_f32_16x16x32_bf16 v[72:75], v[222:225], v[230:233], 0
	ds_read_b128 v[230:233], v246 offset:64
	s_waitcnt lgkmcnt(6)
	v_mfma_f32_16x16x32_bf16 v[80:83], v[222:225], v[234:237], 0
	ds_read_b128 v[234:237], v178 offset:128
	s_waitcnt lgkmcnt(6)
	v_mfma_f32_16x16x32_bf16 v[68:71], v[222:225], v[238:241], 0
	ds_read_b128 v[238:241], v177 offset:34944
	ds_read_b128 v[222:225], v221 offset:128
	s_waitcnt lgkmcnt(6)
	v_mfma_f32_16x16x32_bf16 v[84:87], v[242:245], v[76:79], v[84:87]
	ds_read_b128 v[76:79], v176 offset:34944
	s_waitcnt lgkmcnt(6)
	v_mfma_f32_16x16x32_bf16 v[72:75], v[242:245], v[248:251], v[72:75]
	ds_read_b128 v[248:251], v246 offset:128
	s_waitcnt lgkmcnt(6)
	v_mfma_f32_16x16x32_bf16 v[80:83], v[242:245], v[226:229], v[80:83]
	ds_read_b128 v[226:229], v178 offset:192
	s_waitcnt lgkmcnt(6)
	v_mfma_f32_16x16x32_bf16 v[68:71], v[242:245], v[230:233], v[68:71]
	ds_read_b128 v[230:233], v177 offset:35008
	ds_read_b128 v[242:245], v221 offset:192
	s_waitcnt lgkmcnt(6)
	v_mfma_f32_16x16x32_bf16 v[84:87], v[234:237], v[238:241], v[84:87]
	ds_read_b128 v[238:241], v176 offset:35008
	s_waitcnt lgkmcnt(6)
	v_mfma_f32_16x16x32_bf16 v[72:75], v[234:237], v[222:225], v[72:75]
	ds_read_b128 v[222:225], v246 offset:192
	s_waitcnt lgkmcnt(6)
	v_mfma_f32_16x16x32_bf16 v[80:83], v[234:237], v[76:79], v[80:83]
	ds_read_b128 v[76:79], v178 offset:256
	s_waitcnt lgkmcnt(6)
	v_mfma_f32_16x16x32_bf16 v[68:71], v[234:237], v[248:251], v[68:71]
	ds_read_b128 v[248:251], v177 offset:35072
	ds_read_b128 v[234:237], v221 offset:256
	s_waitcnt lgkmcnt(6)
	v_mfma_f32_16x16x32_bf16 v[84:87], v[226:229], v[230:233], v[84:87]
	ds_read_b128 v[230:233], v176 offset:35072
	s_waitcnt lgkmcnt(6)
	v_mfma_f32_16x16x32_bf16 v[72:75], v[226:229], v[242:245], v[72:75]
	ds_read_b128 v[242:245], v246 offset:256
	s_waitcnt lgkmcnt(6)
	v_mfma_f32_16x16x32_bf16 v[80:83], v[226:229], v[238:241], v[80:83]
	ds_read_b128 v[238:241], v178 offset:320
	s_waitcnt lgkmcnt(6)
	v_mfma_f32_16x16x32_bf16 v[68:71], v[226:229], v[222:225], v[68:71]
	ds_read_b128 v[222:225], v177 offset:35136
	ds_read_b128 v[226:229], v221 offset:320
	s_waitcnt lgkmcnt(6)
	v_mfma_f32_16x16x32_bf16 v[84:87], v[76:79], v[248:251], v[84:87]
	ds_read_b128 v[248:251], v176 offset:35136
	s_waitcnt lgkmcnt(6)
	v_mfma_f32_16x16x32_bf16 v[72:75], v[76:79], v[234:237], v[72:75]
	ds_read_b128 v[234:237], v246 offset:320
	s_waitcnt lgkmcnt(6)
	v_mfma_f32_16x16x32_bf16 v[80:83], v[76:79], v[230:233], v[80:83]
	ds_read_b128 v[230:233], v178 offset:384
	s_waitcnt lgkmcnt(6)
	v_mfma_f32_16x16x32_bf16 v[68:71], v[76:79], v[242:245], v[68:71]
	ds_read_b128 v[242:245], v177 offset:35200
	ds_read_b128 v[76:79], v221 offset:384
	s_waitcnt lgkmcnt(6)
	v_mfma_f32_16x16x32_bf16 v[84:87], v[238:241], v[222:225], v[84:87]
	ds_read_b128 v[222:225], v176 offset:35200
	s_waitcnt lgkmcnt(6)
	v_mfma_f32_16x16x32_bf16 v[72:75], v[238:241], v[226:229], v[72:75]
	ds_read_b128 v[226:229], v246 offset:384
	s_waitcnt lgkmcnt(6)
	v_mfma_f32_16x16x32_bf16 v[80:83], v[238:241], v[248:251], v[80:83]
	ds_read_b128 v[248:251], v178 offset:448
	s_waitcnt lgkmcnt(6)
	v_mfma_f32_16x16x32_bf16 v[68:71], v[238:241], v[234:237], v[68:71]
	ds_read_b128 v[234:237], v177 offset:35264
	ds_read_b128 v[238:241], v221 offset:448
	s_waitcnt lgkmcnt(6)
	v_mfma_f32_16x16x32_bf16 v[84:87], v[230:233], v[242:245], v[84:87]
	ds_read_b128 v[242:245], v176 offset:35264
	s_waitcnt lgkmcnt(6)
	v_mfma_f32_16x16x32_bf16 v[72:75], v[230:233], v[76:79], v[72:75]
	ds_read_b128 v[76:79], v246 offset:448
	s_waitcnt lgkmcnt(6)
	v_mfma_f32_16x16x32_bf16 v[80:83], v[230:233], v[222:225], v[80:83]
	s_waitcnt lgkmcnt(5)
	v_mfma_f32_16x16x32_bf16 v[68:71], v[230:233], v[226:229], v[68:71]
	s_waitcnt lgkmcnt(3)
	v_mfma_f32_16x16x32_bf16 v[84:87], v[248:251], v[234:237], v[84:87]
	s_waitcnt lgkmcnt(2)
	v_mfma_f32_16x16x32_bf16 v[72:75], v[248:251], v[238:241], v[72:75]
	s_waitcnt lgkmcnt(1)
	v_mfma_f32_16x16x32_bf16 v[80:83], v[248:251], v[242:245], v[80:83]
	s_waitcnt lgkmcnt(0)
	v_mfma_f32_16x16x32_bf16 v[68:71], v[248:251], v[76:79], v[68:71]
	s_movk_i32 s21, 0x200
	s_cmpk_lg_i32 s21, 0x200
	ds_read_b128 v[76:79], v191
	ds_read_b32 v194, v167
	ds_read_b32 v221, v168
	ds_read_b32 v222, v169
	ds_read_b32 v223, v170
	ds_read_b32 v224, v188
	s_waitcnt lgkmcnt(4)
	v_sub_f32_e32 v225, v76, v194
	v_exp_f32_e32 v225, v225
	v_sub_f32_e32 v226, v77, v194
	v_exp_f32_e32 v226, v226
	s_lshl_b32 s21, s20, 12
	v_mul_f32_e32 v84, v84, v225
	s_waitcnt lgkmcnt(3)
	v_mul_f32_e32 v84, v221, v84
	v_cvt_pk_bf16_f32 v84, v84, s0
	v_cndmask_b32_e64 v84, v84, 0, s[4:5]
	ds_write_b16 v192, v84
	v_mul_f32_e32 v84, v85, v226
	v_sub_f32_e32 v85, v78, v194
	v_exp_f32_e32 v85, v85
	v_mul_f32_e32 v84, v221, v84
	v_cvt_pk_bf16_f32 v84, v84, s0
	v_cndmask_b32_e64 v84, v84, 0, s[6:7]
	ds_write_b16 v192, v84 offset:144
	v_mul_f32_e32 v84, v86, v85
	v_sub_f32_e32 v85, v79, v194
	v_exp_f32_e32 v85, v85
	v_mul_f32_e32 v84, v221, v84
	v_cvt_pk_bf16_f32 v84, v84, s0
	v_cndmask_b32_e64 v84, v84, 0, s[8:9]
	ds_write_b16 v192, v84 offset:288
	v_mul_f32_e32 v84, v87, v85
	s_waitcnt lgkmcnt(5)
; __device__ __forceinline__ float ex2(float x) { return __builtin_amdgcn_exp2f(x); }
; template <int DK, int MODE>
; __device__ void rec_prompt_item(const Params& p, const int item, unsigned char* smem) {
;     ...
;     for (int x = 0; x < 2; ++x) {
;       const int fj = fe0 + x;
;       const int j = 16 * fj + l15;
;       const float cj = cumS[j], uj = uS[j];
; #pragma unroll
;       for (int r = 0; r < 4; ++r) {
;         const int i = 16 * fi + 4 * g + r;
;         float v = 0.f;
;         if (j <= i) v = sc[x][r] * ex2(ci[r] - cj) * uj;
;         *(u16*)(Ps + i * PS + j * 2) = f2bf(v);
;       }
;     }
;     {
;       const float atot = ex2(cumS[63]);
; #pragma unroll
;       for (int mf = 0; mf < MF; ++mf)
; #pragma unroll
;         for (int nf = 0; nf < 4; ++nf)
; #pragma unroll
;           for (int r = 0; r < 4; ++r) S[mf][nf][r] *= atot;
; #pragma unroll
;       for (int ks = 0; ks < 2; ++ks) {
;         bf16x8 af[MF], bfv[4];
; #pragma unroll
;         for (int mf = 0; mf < MF; ++mf) af[mf] = trfrag(Ks, QS, 32 * ks, dw + 16 * mf, lane);
; #pragma unroll
;         for (int nf = 0; nf < 4; ++nf) bfv[nf] = trfrag(Vts, VS, 32 * ks, 16 * nf, lane);
; #pragma unroll
;         for (int mf = 0; mf < MF; ++mf)
; #pragma unroll
;           for (int nf = 0; nf < 4; ++nf)
;             S[mf][nf] = __builtin_amdgcn_mfma_f32_16x16x32_bf16(af[mf], bfv[nf], S[mf][nf], 0, 0, 0);
;       }
	v_sub_f32_e32 v85, v76, v222
	v_mul_f32_e32 v84, v221, v84
	v_exp_f32_e32 v85, v85
	v_cvt_pk_bf16_f32 v84, v84, s0
	v_cndmask_b32_e64 v84, v84, 0, s[10:11]
	ds_write_b16 v192, v84 offset:432
	v_sub_f32_e32 v84, v77, v222
	v_mul_f32_e32 v80, v80, v85
	v_exp_f32_e32 v84, v84
	s_waitcnt lgkmcnt(5)
	v_mul_f32_e32 v80, v223, v80
	v_cvt_pk_bf16_f32 v80, v80, s0
	v_cndmask_b32_e64 v80, v80, 0, s[12:13]
	ds_write_b16 v193, v80
	v_mul_f32_e32 v80, v81, v84
	v_sub_f32_e32 v81, v78, v222
	v_exp_f32_e32 v81, v81
	v_mul_f32_e32 v80, v223, v80
	v_cvt_pk_bf16_f32 v80, v80, s0
	v_cndmask_b32_e64 v80, v80, 0, s[14:15]
	ds_write_b16 v193, v80 offset:144
	v_mul_f32_e32 v80, v82, v81
	v_sub_f32_e32 v81, v79, v222
	v_exp_f32_e32 v81, v81
	v_mul_f32_e32 v80, v223, v80
	v_cvt_pk_bf16_f32 v80, v80, s0
	v_cndmask_b32_e64 v80, v80, 0, s[16:17]
	ds_write_b16 v193, v80 offset:288
	v_mul_f32_e32 v80, v83, v81
	v_mul_f32_e32 v80, v223, v80
	v_cvt_pk_bf16_f32 v80, v80, s0
	v_cndmask_b32_e64 v80, v80, 0, s[18:19]
	ds_write_b16 v193, v80 offset:432
	s_waitcnt lgkmcnt(8)
	v_exp_f32_e32 v194, v224
	ds_read_b64_tr_b16 v[82:83], v195 offset:36992
	ds_read_b64_tr_b16 v[80:81], v195 offset:34816
	ds_read_b64_tr_b16 v[86:87], v195 offset:37024
	ds_read_b64_tr_b16 v[84:85], v195 offset:34848
	ds_read_b64_tr_b16 v[224:225], v196 offset:640
	ds_read_b64_tr_b16 v[222:223], v196
	ds_read_b64_tr_b16 v[226:227], v196 offset:32
	ds_read_b64_tr_b16 v[230:231], v196 offset:64
	ds_read_b64_tr_b16 v[234:235], v196 offset:96
	ds_read_b64_tr_b16 v[228:229], v196 offset:672
	ds_read_b64_tr_b16 v[232:233], v196 offset:704
	ds_read_b64_tr_b16 v[236:237], v196 offset:736
	s_add_u32 s44, s33, s21
	s_addc_u32 s45, s34, 0
	v_pk_mul_f32 v[66:67], v[66:67], v[194:195] op_sel_hi:[1,0]
	v_pk_mul_f32 v[64:65], v[64:65], v[194:195] op_sel_hi:[1,0]
	v_pk_mul_f32 v[62:63], v[62:63], v[194:195] op_sel_hi:[1,0]
	v_pk_mul_f32 v[60:61], v[60:61], v[194:195] op_sel_hi:[1,0]
	v_pk_mul_f32 v[58:59], v[58:59], v[194:195] op_sel_hi:[1,0]
	v_pk_mul_f32 v[56:57], v[56:57], v[194:195] op_sel_hi:[1,0]
	v_pk_mul_f32 v[54:55], v[54:55], v[194:195] op_sel_hi:[1,0]
	v_pk_mul_f32 v[52:53], v[52:53], v[194:195] op_sel_hi:[1,0]
	v_pk_mul_f32 v[50:51], v[50:51], v[194:195] op_sel_hi:[1,0]
	v_pk_mul_f32 v[48:49], v[48:49], v[194:195] op_sel_hi:[1,0]
	v_pk_mul_f32 v[42:43], v[42:43], v[194:195] op_sel_hi:[1,0]
	v_pk_mul_f32 v[40:41], v[40:41], v[194:195] op_sel_hi:[1,0]
	v_pk_mul_f32 v[38:39], v[38:39], v[194:195] op_sel_hi:[1,0]
	v_pk_mul_f32 v[36:37], v[36:37], v[194:195] op_sel_hi:[1,0]
	v_pk_mul_f32 v[46:47], v[46:47], v[194:195] op_sel_hi:[1,0]
	v_pk_mul_f32 v[44:45], v[44:45], v[194:195] op_sel_hi:[1,0]
	s_waitcnt lgkmcnt(6)
	v_mfma_f32_16x16x32_bf16 v[64:67], v[80:83], v[222:225], v[64:67]
	v_lshlrev_b32_e32 v194, 16, v216
	v_mul_f32_e32 v216, 0xbfb8aa3b, v194
	v_exp_f32_e32 v216, v216
	s_waitcnt lgkmcnt(2)
	v_mfma_f32_16x16x32_bf16 v[60:63], v[80:83], v[226:229], v[60:63]
	s_waitcnt lgkmcnt(1)
	v_mfma_f32_16x16x32_bf16 v[56:59], v[80:83], v[230:233], v[56:59]
	s_waitcnt lgkmcnt(0)
	v_mfma_f32_16x16x32_bf16 v[52:55], v[80:83], v[234:237], v[52:55]
	v_mfma_f32_16x16x32_bf16 v[48:51], v[84:87], v[222:225], v[48:51]
	v_mfma_f32_16x16x32_bf16 v[40:43], v[84:87], v[226:229], v[40:43]
	v_mfma_f32_16x16x32_bf16 v[36:39], v[84:87], v[230:233], v[36:39]
	v_mfma_f32_16x16x32_bf16 v[80:83], v[84:87], v[234:237], v[44:47]
	s_nop 2
	ds_read_b64_tr_b16 v[46:47], v197 offset:36992
	ds_read_b64_tr_b16 v[44:45], v197 offset:34816
	ds_read_b64_tr_b16 v[86:87], v197 offset:37024
	ds_read_b64_tr_b16 v[84:85], v197 offset:34848
	ds_read_b64_tr_b16 v[224:225], v196 offset:5760
	ds_read_b64_tr_b16 v[222:223], v196 offset:5120
	ds_read_b64_tr_b16 v[226:227], v196 offset:5152
	ds_read_b64_tr_b16 v[230:231], v196 offset:5184
	ds_read_b64_tr_b16 v[234:235], v196 offset:5216
	ds_read_b64_tr_b16 v[228:229], v196 offset:5792
	ds_read_b64_tr_b16 v[232:233], v196 offset:5824
	ds_read_b64_tr_b16 v[236:237], v196 offset:5856
	s_waitcnt lgkmcnt(0)
	s_barrier
; template <int DK, int MODE>
; __device__ void rec_prompt_item(const Params& p, const int item, unsigned char* smem) {
;     ...
;         for (int mf = 0; mf < MF; ++mf) af[mf] = trfrag(Ks, QS, 32 * ks, dw + 16 * mf, lane);
; #pragma unroll
;         for (int nf = 0; nf < 4; ++nf) bfv[nf] = trfrag(Vts, VS, 32 * ks, 16 * nf, lane);
; #pragma unroll
;         for (int mf = 0; mf < MF; ++mf)
; #pragma unroll
;           for (int nf = 0; nf < 4; ++nf)
;             S[mf][nf] = __builtin_amdgcn_mfma_f32_16x16x32_bf16(af[mf], bfv[nf], S[mf][nf], 0, 0, 0);
;       }
;     }
;     __syncthreads();
;     f32x4 in[2];
; #pragma unroll
;     for (int x = 0; x < 2; ++x) in[x] = (f32x4){0.f, 0.f, 0.f, 0.f};
; #pragma unroll
;     for (int ks = 0; ks < 2; ++ks) {
;       const bf16x8 a = *(const bf16x8*)(Ps + (16 * fi + l15) * PS + ks * 64 + g * 16);
;       bf16x8 bv[2];
; #pragma unroll
;       for (int x = 0; x < 2; ++x) bv[x] = trfrag(Vs, VS, 32 * ks, 16 * (fe0 + x), lane);
; #pragma unroll
;       for (int x = 0; x < 2; ++x) in[x] = __builtin_amdgcn_mfma_f32_16x16x32_bf16(a, bv[x], in[x], 0, 0, 0);
;     }
;     {
;       float ss[4] = {0.f, 0.f, 0.f, 0.f};
;       u16* aout = (u16*)(p.ws + OFF_A2);
;       float* parts = (float*)(p.ws + OFF_PARTS);
; #pragma unroll
;       for (int x = 0; x < 2; ++x) {
;         const int e = 16 * (fe0 + x) + l15;
;         const float gn = gnv[x];
;         const int ocol = (MODE == 0) ? (h * 512 + s * 64 + e) : (h * 64 + e);
; #pragma unroll
;         for (int r = 0; r < 4; ++r) {
;           const int i = 16 * fi + 4 * g + r;
;           float o = in[x][r] + cr[x][r] * ex2(ci[r]);
;           const float gv = bf2f(gzc[x][r]);
;           float val;
;           if (MODE == 0) {
;             ss[r] += o * o;
;             val = o * gn * silu(gv);
;           } else {
;             const float xs = bf2f(*(const u16*)(Vs + i * VS + e * 2));
;             const float y = o + xs * dsk;
;             const float gg = y * silu(gv);
;             ss[r] += gg * gg;
;             val = gg * gn;
;           }
;           *(u16*)((char*)aout + (size_t)r0 * 4096 + 32 * x + aoff[r]) = f2bf(val);
;         }
;       }
; #pragma unroll
;       for (int r = 0; r < 4; ++r) {
;         const float v = row16_sum(ss[r]);
;         if (l15 == 0) {
;           const int i = 16 * fi + 4 * g + r;
	v_mfma_f32_16x16x32_bf16 v[64:67], v[44:47], v[222:225], v[64:67]
	v_mfma_f32_16x16x32_bf16 v[60:63], v[44:47], v[226:229], v[60:63]
	v_mfma_f32_16x16x32_bf16 v[56:59], v[44:47], v[230:233], v[56:59]
	v_mfma_f32_16x16x32_bf16 v[52:55], v[44:47], v[234:237], v[52:55]
	v_mfma_f32_16x16x32_bf16 v[48:51], v[84:87], v[222:225], v[48:51]
	v_mfma_f32_16x16x32_bf16 v[44:47], v[84:87], v[226:229], v[40:43]
	ds_read_b128 v[222:225], v198
	ds_read_b64_tr_b16 v[226:227], v217
	ds_read_b64_tr_b16 v[228:229], v217 offset:640
	v_mfma_f32_16x16x32_bf16 v[40:43], v[84:87], v[230:233], v[36:39]
	v_mfma_f32_16x16x32_bf16 v[36:39], v[84:87], v[234:237], v[80:83]
	s_nop 2
	ds_read_b64_tr_b16 v[80:81], v218
	ds_read_b64_tr_b16 v[82:83], v218 offset:640
	ds_read_b128 v[84:87], v198 offset:64
	s_waitcnt lgkmcnt(3)
	v_mfma_f32_16x16x32_bf16 v[226:229], v[222:225], v[226:229], 0
	s_waitcnt lgkmcnt(1)
	v_mfma_f32_16x16x32_bf16 v[222:225], v[222:225], v[80:83], 0
	ds_read_b64_tr_b16 v[80:81], v219
	ds_read_b64_tr_b16 v[82:83], v219 offset:640
	ds_read_b64_tr_b16 v[218:219], v220
	ds_read_b64_tr_b16 v[220:221], v220 offset:640
	s_waitcnt lgkmcnt(2)
	v_mfma_f32_16x16x32_bf16 v[80:83], v[84:87], v[80:83], v[226:229]
	s_waitcnt lgkmcnt(0)
	v_mfma_f32_16x16x32_bf16 v[84:87], v[84:87], v[218:221], v[222:225]
	v_exp_f32_e32 v218, v76
	v_add_f32_e32 v76, 1.0, v216
	v_rcp_f32_e32 v76, v76
	v_lshl_add_u64 v[216:217], s[44:45], 0, v[134:135]
	s_nop 1
	v_fma_f32 v219, v72, v218, v80
	v_mul_f32_e32 v72, v117, v219
	v_mul_f32_e32 v76, v76, v194
	v_mul_f32_e32 v72, v76, v72
	v_lshlrev_b32_e32 v76, 16, v215
	v_mul_f32_e32 v80, 0xbfb8aa3b, v76
	v_exp_f32_e32 v80, v80
	v_exp_f32_e32 v194, v77
	v_cvt_pk_bf16_f32 v72, v72, s0
	global_store_short v[216:217], v72, off
	v_add_f32_e32 v77, 1.0, v80
	v_rcp_f32_e32 v77, v77
	v_fma_f32 v73, v73, v194, v81
	v_mul_f32_e32 v72, v117, v73
	v_lshlrev_b32_e32 v80, 16, v214
	v_mul_f32_e32 v76, v77, v76
	v_mul_f32_e32 v72, v76, v72
	v_mul_f32_e32 v76, 0xbfb8aa3b, v80
	v_exp_f32_e32 v81, v76
	v_exp_f32_e32 v214, v78
	v_cvt_pk_bf16_f32 v72, v72, s0
	v_lshl_add_u64 v[76:77], s[44:45], 0, v[136:137]
	v_add_f32_e32 v78, 1.0, v81
	v_rcp_f32_e32 v78, v78
	global_store_short v[76:77], v72, off
	v_fma_f32 v72, v74, v214, v82
	v_mul_f32_e32 v74, v117, v72
	v_mul_f32_e32 v78, v78, v80
	v_mul_f32_e32 v74, v78, v74
	v_lshlrev_b32_e32 v78, 16, v213
	v_mul_f32_e32 v80, 0xbfb8aa3b, v78
	v_exp_f32_e32 v82, v80
	v_exp_f32_e32 v213, v79
	v_cvt_pk_bf16_f32 v74, v74, s0
	v_lshl_add_u64 v[80:81], s[44:45], 0, v[138:139]
	v_add_f32_e32 v79, 1.0, v82
	v_rcp_f32_e32 v79, v79
	v_fmac_f32_e32 v83, v75, v213
	global_store_short v[80:81], v74, off
	v_mul_f32_e32 v74, v117, v83
	v_mul_f32_e32 v75, v79, v78
	v_mul_f32_e32 v74, v75, v74
	v_cvt_pk_bf16_f32 v74, v74, s0
	v_lshl_add_u64 v[78:79], s[44:45], 0, v[140:141]
	global_store_short v[78:79], v74, off
	v_lshlrev_b32_e32 v74, 16, v212
	v_mul_f32_e32 v75, 0xbfb8aa3b, v74
	v_exp_f32_e32 v75, v75
	v_fma_f32 v68, v68, v218, v84
	v_lshlrev_b32_e32 v84, 16, v211
	v_mul_f32_e32 v211, 0xbfb8aa3b, v84
	v_add_f32_e32 v75, 1.0, v75
	v_rcp_f32_e32 v75, v75
	v_exp_f32_e32 v211, v211
	v_mul_f32_e32 v82, v68, v68
	v_mul_f32_e32 v68, v199, v68
	v_mul_f32_e32 v74, v75, v74
	v_mul_f32_e32 v68, v74, v68
	v_add_f32_e32 v74, 1.0, v211
	v_rcp_f32_e32 v75, v74
	v_cvt_pk_bf16_f32 v68, v68, s0
	v_fma_f32 v74, v69, v194, v85
	global_store_short v[216:217], v68, off offset:32
	v_mul_f32_e32 v68, v199, v74
	v_mul_f32_e32 v69, v75, v84
	v_mul_f32_e32 v68, v69, v68
	v_lshlrev_b32_e32 v69, 16, v210
	v_mul_f32_e32 v75, 0xbfb8aa3b, v69
	v_exp_f32_e32 v75, v75
	v_cvt_pk_bf16_f32 v68, v68, s0
	global_store_short v[76:77], v68, off offset:32
	v_lshlrev_b32_e32 v76, 16, v209
	v_add_f32_e32 v75, 1.0, v75
	v_rcp_f32_e32 v75, v75
	v_mul_f32_e32 v77, 0xbfb8aa3b, v76
	v_exp_f32_e32 v77, v77
	v_fma_f32 v70, v70, v214, v86
	v_mul_f32_e32 v68, v199, v70
	v_mul_f32_e32 v69, v75, v69
	v_mul_f32_e32 v68, v69, v68
	v_add_f32_e32 v69, 1.0, v77
	v_rcp_f32_e32 v69, v69
	v_cvt_pk_bf16_f32 v68, v68, s0
	v_fmac_f32_e32 v87, v71, v213
	v_fmac_f32_e32 v82, v219, v219
	global_store_short v[80:81], v68, off offset:32
	v_mul_f32_e32 v68, v199, v87
	v_mul_f32_e32 v69, v69, v76
	v_mul_f32_e32 v68, v69, v68
	v_cvt_pk_bf16_f32 v68, v68, s0
	v_add_f32_dpp v69, v82, v82 quad_perm:[1,0,3,2] row_mask:0xf bank_mask:0xf bound_ctrl:1
	global_store_short v[78:79], v68, off offset:32
	v_add_u32_e32 v68, s20, v91
	v_add_f32_dpp v69, v69, v69 quad_perm:[2,3,0,1] row_mask:0xf bank_mask:0xf bound_ctrl:1
	s_nop 1
	v_add_f32_dpp v71, v69, v69 row_ror:4 row_mask:0xf bank_mask:0xf bound_ctrl:1
	s_nop 1
	v_mov_b32_dpp v75, v71 row_ror:8 row_mask:0xf bank_mask:0xf bound_ctrl:1
	s_and_saveexec_b64 s[20:21], s[2:3]
	s_cbranch_execz .LBB0_440
	v_ashrrev_i32_e32 v69, 31, v68
	v_lshlrev_b64 v[76:77], 8, v[68:69]
	v_lshl_add_u64 v[76:77], v[144:145], 0, v[76:77]
	v_add_f32_e32 v69, v71, v75
	global_store_dword v[76:77], v69, off
